# nt hint on the attention phase's read-once Q and gate loads (keeps the attention output resident for the out-projection)
# speedup vs baseline: 1.0027x; 1.0027x over previous
; DI bf16_t f2bf(float f) { return (bf16_t)(cvt_pk_bf16(f, f) & 0xffffu); }
; DI int crow(int r, int hi) { return (r & 3) + 8 * (r >> 2) + 4 * hi; }
; DI void attn_dense_body(const bf16_t* __restrict__ Qb, const bf16_t* __restrict__ Kh, const bf16_t* __restrict__ Vh, ...
;     ...
;   if (hi == 0) li_l[r32] = l_reg; asm volatile("s_waitcnt lgkmcnt(0)" ::: "memory");
;   float rli[16];
; #pragma unroll
;   for (int r = 0; r < 16; ++r) rli[r] = __builtin_amdgcn_rcpf(li_l[crow(r, hi)]);
;   u32x4 gv[8];
; #pragma unroll
;   for (int it = 0; it < 8; ++it) gv[it] = *(const u32x4*)(Gb + (long)((tid >> 4) + 32 * it) * LDQ + (tid & 15) * 8);
;   __syncthreads();
;   bf16_t* stg = (bf16_t*)lds;
; #pragma unroll
;   for (int r = 0; r < 16; ++r) { bf16_t* sp = stg + (wid * QBLK + crow(r, hi)) * 136 + r32;
;     sp[0] = f2bf(o[0][r] * rli[r]); sp[32] = f2bf(o[1][r] * rli[r]); sp[64] = f2bf(o[2][r] * rli[r]); sp[96] = f2bf(o[3][r] * rli[r]); }
.LBB0_822:
	s_or_b64 exec, exec, s[0:1]
	s_waitcnt lgkmcnt(0)
	v_add_u32_e32 v72, v198, v180
	ds_read_b128 v[64:67], v72
	ds_read_b128 v[68:71], v72 offset:32
	s_add_u32 s0, s56, s8
	s_addc_u32 s1, s57, s9
	v_lshlrev_b32_e32 v180, 1, v178
	s_waitcnt lgkmcnt(1)
	v_rcp_f32_e32 v112, v64
	v_rcp_f32_e32 v113, v65
	v_rcp_f32_e32 v114, v66
	v_rcp_f32_e32 v115, v67
	ds_read_b128 v[64:67], v72 offset:64
	s_waitcnt lgkmcnt(1)
	v_rcp_f32_e32 v116, v68
	v_rcp_f32_e32 v117, v69
	v_rcp_f32_e32 v118, v70
	v_rcp_f32_e32 v119, v71
	ds_read_b128 v[68:71], v72 offset:96
	s_waitcnt lgkmcnt(1)
	v_rcp_f32_e32 v120, v64
	v_rcp_f32_e32 v121, v65
	v_lshl_add_u64 v[64:65], s[0:1], 0, v[180:181]
	v_lshlrev_b64 v[110:111], 11, v[176:177]
	v_rcp_f32_e32 v122, v66
	v_rcp_f32_e32 v123, v67
	v_lshl_add_u64 v[66:67], v[64:65], 0, v[110:111]
	v_lshlrev_b64 v[108:109], 11, v[184:185]
	v_lshlrev_b64 v[106:107], 11, v[186:187]
	s_mov_b64 s[0:1], 0x60000
	s_waitcnt lgkmcnt(0)
	v_rcp_f32_e32 v124, v68
	v_rcp_f32_e32 v125, v69
	v_lshl_add_u64 v[68:69], v[64:65], 0, v[108:109]
	global_load_dwordx4 v[92:95], v[66:67], off nt
	global_load_dwordx4 v[88:91], v[68:69], off nt
	v_lshl_add_u64 v[66:67], v[64:65], 0, v[106:107]
	v_lshlrev_b64 v[104:105], 11, v[188:189]
	v_lshlrev_b64 v[102:103], 11, v[190:191]
	v_lshl_add_u64 v[98:99], v[110:111], 0, s[0:1]
	s_mov_b64 s[0:1], 0x70000
	v_lshl_add_u64 v[68:69], v[64:65], 0, v[104:105]
	global_load_dwordx4 v[84:87], v[66:67], off nt
	global_load_dwordx4 v[80:83], v[68:69], off nt
	v_lshl_add_u64 v[66:67], v[64:65], 0, v[102:103]
	v_lshlrev_b64 v[100:101], 11, v[192:193]
	v_lshl_add_u64 v[96:97], v[110:111], 0, s[0:1]
	v_lshl_or_b32 v128, v179, 2, v197
	s_movk_i32 s0, 0x110
	v_lshl_add_u64 v[68:69], v[64:65], 0, v[100:101]
	global_load_dwordx4 v[76:79], v[66:67], off nt
	global_load_dwordx4 v[72:75], v[68:69], off nt
	v_lshl_add_u64 v[66:67], v[64:65], 0, v[98:99]
	v_lshl_add_u64 v[64:65], v[64:65], 0, v[96:97]
	v_lshlrev_b32_e32 v129, 1, v196
	v_mul_lo_u32 v128, v128, s0
	v_mul_f32_e32 v0, v0, v112
	v_rcp_f32_e32 v126, v70
	v_rcp_f32_e32 v127, v71
	global_load_dwordx4 v[68:71], v[66:67], off nt
	s_nop 0
	global_load_dwordx4 v[64:67], v[64:65], off nt
	s_barrier
	v_add3_u32 v128, 0, v129, v128
	v_cvt_pk_bf16_f32 v0, v0, v0
	ds_write_b16 v128, v0
	v_mul_f32_e32 v0, v48, v112
	v_cvt_pk_bf16_f32 v0, v0, v0
	ds_write_b16 v128, v0 offset:64
	v_mul_f32_e32 v0, v32, v112
	v_cvt_pk_bf16_f32 v0, v0, v0
	ds_write_b16 v128, v0 offset:128
	v_mul_f32_e32 v0, v16, v112
	v_cvt_pk_bf16_f32 v0, v0, v0
	ds_write_b16 v128, v0 offset:192
	v_mul_f32_e32 v0, v1, v113
	v_cvt_pk_bf16_f32 v0, v0, v0
	ds_write_b16 v128, v0 offset:272
	v_mul_f32_e32 v0, v49, v113
	v_cvt_pk_bf16_f32 v0, v0, v0
	ds_write_b16 v128, v0 offset:336
	v_mul_f32_e32 v0, v33, v113
	v_cvt_pk_bf16_f32 v0, v0, v0
	ds_write_b16 v128, v0 offset:400
	v_mul_f32_e32 v0, v17, v113
	v_cvt_pk_bf16_f32 v0, v0, v0
	ds_write_b16 v128, v0 offset:464
	v_mul_f32_e32 v0, v2, v114
	v_cvt_pk_bf16_f32 v0, v0, v0
	ds_write_b16 v128, v0 offset:544
	v_mul_f32_e32 v0, v50, v114
	v_cvt_pk_bf16_f32 v0, v0, v0
	ds_write_b16 v128, v0 offset:608
	v_mul_f32_e32 v0, v34, v114
	v_cvt_pk_bf16_f32 v0, v0, v0
	ds_write_b16 v128, v0 offset:672
	v_mul_f32_e32 v0, v18, v114
	v_cvt_pk_bf16_f32 v0, v0, v0
	ds_write_b16 v128, v0 offset:736
	v_mul_f32_e32 v0, v3, v115
	v_cvt_pk_bf16_f32 v0, v0, v0
	ds_write_b16 v128, v0 offset:816
	v_mul_f32_e32 v0, v51, v115
	v_cvt_pk_bf16_f32 v0, v0, v0
	ds_write_b16 v128, v0 offset:880
	v_mul_f32_e32 v0, v35, v115
	v_cvt_pk_bf16_f32 v0, v0, v0
	ds_write_b16 v128, v0 offset:944
	v_mul_f32_e32 v0, v19, v115
	v_cvt_pk_bf16_f32 v0, v0, v0
	ds_write_b16 v128, v0 offset:1008
	v_mul_f32_e32 v0, v4, v116
	v_cvt_pk_bf16_f32 v0, v0, v0
	ds_write_b16 v128, v0 offset:2176
	v_mul_f32_e32 v0, v52, v116
	v_cvt_pk_bf16_f32 v0, v0, v0
	ds_write_b16 v128, v0 offset:2240
	v_mul_f32_e32 v0, v36, v116
	v_cvt_pk_bf16_f32 v0, v0, v0
	ds_write_b16 v128, v0 offset:2304
	v_mul_f32_e32 v0, v20, v116
	v_cvt_pk_bf16_f32 v0, v0, v0
	ds_write_b16 v128, v0 offset:2368
	v_mul_f32_e32 v0, v5, v117
	v_cvt_pk_bf16_f32 v0, v0, v0
	ds_write_b16 v128, v0 offset:2448
	v_mul_f32_e32 v0, v53, v117
	v_cvt_pk_bf16_f32 v0, v0, v0
	ds_write_b16 v128, v0 offset:2512
	v_mul_f32_e32 v0, v37, v117
	v_cvt_pk_bf16_f32 v0, v0, v0
	ds_write_b16 v128, v0 offset:2576
	v_mul_f32_e32 v0, v21, v117
	v_cvt_pk_bf16_f32 v0, v0, v0
	ds_write_b16 v128, v0 offset:2640
	v_mul_f32_e32 v0, v6, v118
	v_cvt_pk_bf16_f32 v0, v0, v0
	ds_write_b16 v128, v0 offset:2720
	v_mul_f32_e32 v0, v54, v118
	v_cvt_pk_bf16_f32 v0, v0, v0
	ds_write_b16 v128, v0 offset:2784
	v_mul_f32_e32 v0, v38, v118
	v_cvt_pk_bf16_f32 v0, v0, v0
	ds_write_b16 v128, v0 offset:2848
	v_mul_f32_e32 v0, v22, v118
	v_cvt_pk_bf16_f32 v0, v0, v0
	ds_write_b16 v128, v0 offset:2912
	v_mul_f32_e32 v0, v7, v119
	v_cvt_pk_bf16_f32 v0, v0, v0
	ds_write_b16 v128, v0 offset:2992
	v_mul_f32_e32 v0, v55, v119
	v_cvt_pk_bf16_f32 v0, v0, v0
	ds_write_b16 v128, v0 offset:3056
	v_mul_f32_e32 v0, v39, v119
	v_cvt_pk_bf16_f32 v0, v0, v0
	ds_write_b16 v128, v0 offset:3120
	v_mul_f32_e32 v0, v23, v119
	v_cvt_pk_bf16_f32 v0, v0, v0
	ds_write_b16 v128, v0 offset:3184
	v_mul_f32_e32 v0, v8, v120
	v_cvt_pk_bf16_f32 v0, v0, v0
	ds_write_b16 v128, v0 offset:4352
	v_mul_f32_e32 v0, v56, v120
	v_cvt_pk_bf16_f32 v0, v0, v0
	ds_write_b16 v128, v0 offset:4416
	v_mul_f32_e32 v0, v40, v120
	v_cvt_pk_bf16_f32 v0, v0, v0
	ds_write_b16 v128, v0 offset:4480
	v_mul_f32_e32 v0, v24, v120
	v_cvt_pk_bf16_f32 v0, v0, v0
	ds_write_b16 v128, v0 offset:4544
	v_mul_f32_e32 v0, v9, v121
	v_cvt_pk_bf16_f32 v0, v0, v0
	ds_write_b16 v128, v0 offset:4624
; DI float bflo(unsigned w) { return __uint_as_float(w << 16); }
; DI float bfhi(unsigned w) { return __uint_as_float(w & 0xffff0000u); }
; DI bf16_t f2bf(float f) { return (bf16_t)(cvt_pk_bf16(f, f) & 0xffffu); }
; DI void store8(bf16_t* p, f32x4 a, f32x4 b) { u32x4 w = {cvt_pk_bf16(a[0], a[1]), cvt_pk_bf16(a[2], a[3]), cvt_pk_bf16(b[0], b[1]), cvt_pk_bf16(b[2], b[3])}; *(u32x4*)p = w; }
; DI int crow(int r, int hi) { return (r & 3) + 8 * (r >> 2) + 4 * hi; }
; DI void attn_dense_body(const bf16_t* __restrict__ Qb, const bf16_t* __restrict__ Kh, const bf16_t* __restrict__ Vh, ...
;     ...
;   for (int r = 0; r < 16; ++r) { bf16_t* sp = stg + (wid * QBLK + crow(r, hi)) * 136 + r32;
;     sp[0] = f2bf(o[0][r] * rli[r]); sp[32] = f2bf(o[1][r] * rli[r]); sp[64] = f2bf(o[2][r] * rli[r]); sp[96] = f2bf(o[3][r] * rli[r]); }
;   __syncthreads();
; #pragma unroll
;   for (int it = 0; it < 8; ++it) { const int row = (tid >> 4) + 32 * it, c8 = (tid & 15) * 8;
;     const u32x4 ov = *(const u32x4*)(stg + row * 136 + c8);
;     f32x4 y0, y1;
;     y0[0] = bflo(ov[0]) * bflo(gv[it][0]); y0[1] = bfhi(ov[0]) * bfhi(gv[it][0]); y0[2] = bflo(ov[1]) * bflo(gv[it][1]); y0[3] = bfhi(ov[1]) * bfhi(gv[it][1]);
;     y1[0] = bflo(ov[2]) * bflo(gv[it][2]); y1[1] = bfhi(ov[2]) * bfhi(gv[it][2]); y1[2] = bflo(ov[3]) * bflo(gv[it][3]); y1[3] = bfhi(ov[3]) * bfhi(gv[it][3]);
;     store8(Ob + (long)row * LDQ + c8, y0, y1); }
	v_mul_f32_e32 v0, v57, v121
	v_cvt_pk_bf16_f32 v0, v0, v0
	ds_write_b16 v128, v0 offset:4688
	v_mul_f32_e32 v0, v41, v121
	v_cvt_pk_bf16_f32 v0, v0, v0
	ds_write_b16 v128, v0 offset:4752
	v_mul_f32_e32 v0, v25, v121
	v_cvt_pk_bf16_f32 v0, v0, v0
	ds_write_b16 v128, v0 offset:4816
	v_mul_f32_e32 v0, v10, v122
	v_cvt_pk_bf16_f32 v0, v0, v0
	ds_write_b16 v128, v0 offset:4896
	v_mul_f32_e32 v0, v58, v122
	v_cvt_pk_bf16_f32 v0, v0, v0
	ds_write_b16 v128, v0 offset:4960
	v_mul_f32_e32 v0, v42, v122
	v_cvt_pk_bf16_f32 v0, v0, v0
	ds_write_b16 v128, v0 offset:5024
	v_mul_f32_e32 v0, v26, v122
	v_cvt_pk_bf16_f32 v0, v0, v0
	ds_write_b16 v128, v0 offset:5088
	v_mul_f32_e32 v0, v11, v123
	v_cvt_pk_bf16_f32 v0, v0, v0
	ds_write_b16 v128, v0 offset:5168
	v_mul_f32_e32 v0, v59, v123
	v_cvt_pk_bf16_f32 v0, v0, v0
	ds_write_b16 v128, v0 offset:5232
	v_mul_f32_e32 v0, v43, v123
	v_cvt_pk_bf16_f32 v0, v0, v0
	ds_write_b16 v128, v0 offset:5296
	v_mul_f32_e32 v0, v27, v123
	v_cvt_pk_bf16_f32 v0, v0, v0
	ds_write_b16 v128, v0 offset:5360
	v_mul_f32_e32 v0, v12, v124
	v_cvt_pk_bf16_f32 v0, v0, v0
	ds_write_b16 v128, v0 offset:6528
	v_mul_f32_e32 v0, v60, v124
	v_cvt_pk_bf16_f32 v0, v0, v0
	ds_write_b16 v128, v0 offset:6592
	v_mul_f32_e32 v0, v44, v124
	v_cvt_pk_bf16_f32 v0, v0, v0
	ds_write_b16 v128, v0 offset:6656
	v_mul_f32_e32 v0, v28, v124
	v_cvt_pk_bf16_f32 v0, v0, v0
	ds_write_b16 v128, v0 offset:6720
	v_mul_f32_e32 v0, v13, v125
	v_cvt_pk_bf16_f32 v0, v0, v0
	ds_write_b16 v128, v0 offset:6800
	v_mul_f32_e32 v0, v61, v125
	v_cvt_pk_bf16_f32 v0, v0, v0
	ds_write_b16 v128, v0 offset:6864
	v_mul_f32_e32 v0, v45, v125
	v_cvt_pk_bf16_f32 v0, v0, v0
	ds_write_b16 v128, v0 offset:6928
	v_mul_f32_e32 v0, v29, v125
	v_cvt_pk_bf16_f32 v0, v0, v0
	ds_write_b16 v128, v0 offset:6992
	v_mul_f32_e32 v0, v14, v126
	v_cvt_pk_bf16_f32 v0, v0, v0
	ds_write_b16 v128, v0 offset:7072
	v_mul_f32_e32 v0, v62, v126
	v_cvt_pk_bf16_f32 v0, v0, v0
	ds_write_b16 v128, v0 offset:7136
	v_mul_f32_e32 v0, v46, v126
	v_cvt_pk_bf16_f32 v0, v0, v0
	ds_write_b16 v128, v0 offset:7200
	v_mul_f32_e32 v0, v30, v126
	v_cvt_pk_bf16_f32 v0, v0, v0
	ds_write_b16 v128, v0 offset:7264
	v_mul_f32_e32 v0, v15, v127
	v_cvt_pk_bf16_f32 v0, v0, v0
	ds_write_b16 v128, v0 offset:7344
	v_mul_f32_e32 v0, v63, v127
	v_cvt_pk_bf16_f32 v0, v0, v0
	ds_write_b16 v128, v0 offset:7408
	v_mul_f32_e32 v0, v47, v127
	v_cvt_pk_bf16_f32 v0, v0, v0
	ds_write_b16 v128, v0 offset:7472
	v_mul_f32_e32 v0, v31, v127
	v_cvt_pk_bf16_f32 v0, v0, v0
	ds_write_b16 v128, v0 offset:7536
	v_mul_lo_u32 v0, v176, s0
	v_add3_u32 v12, 0, v180, v0
	s_waitcnt lgkmcnt(0)
	s_barrier
	ds_read_b128 v[0:3], v12
	s_waitcnt vmcnt(7)
	v_lshlrev_b32_e32 v4, 16, v92
	s_add_u32 s0, s58, s8
	s_addc_u32 s1, s59, s9
	s_add_i32 s14, s14, s30
	s_waitcnt lgkmcnt(0)
	v_lshlrev_b32_e32 v5, 16, v0
	v_mul_f32_e32 v4, v5, v4
	v_and_b32_e32 v0, 0xffff0000, v0
	v_and_b32_e32 v5, 0xffff0000, v92
	v_mul_f32_e32 v0, v0, v5
	v_lshlrev_b32_e32 v5, 16, v93
	v_lshlrev_b32_e32 v6, 16, v1
	v_mul_f32_e32 v5, v6, v5
	v_and_b32_e32 v1, 0xffff0000, v1
	v_and_b32_e32 v6, 0xffff0000, v93
	v_mul_f32_e32 v1, v1, v6
	v_lshlrev_b32_e32 v6, 16, v94
	v_lshlrev_b32_e32 v7, 16, v2
	v_mul_f32_e32 v6, v7, v6
	v_and_b32_e32 v2, 0xffff0000, v2
	v_and_b32_e32 v7, 0xffff0000, v94
	v_mul_f32_e32 v2, v2, v7
	v_lshlrev_b32_e32 v7, 16, v95
	v_lshlrev_b32_e32 v8, 16, v3
	v_mul_f32_e32 v7, v8, v7
	v_and_b32_e32 v3, 0xffff0000, v3
	v_and_b32_e32 v8, 0xffff0000, v95
	v_mul_f32_e32 v3, v3, v8
	v_cvt_pk_bf16_f32 v0, v4, v0
	v_cvt_pk_bf16_f32 v1, v5, v1
	v_cvt_pk_bf16_f32 v2, v6, v2
	v_cvt_pk_bf16_f32 v3, v7, v3
	ds_read_b128 v[4:7], v12 offset:8704
	v_lshl_add_u64 v[8:9], s[0:1], 0, v[180:181]
	v_lshl_add_u64 v[10:11], v[8:9], 0, v[110:111]
	global_store_dwordx4 v[10:11], v[0:3], off
	s_cmpk_lt_i32 s14, 0x440
	s_waitcnt lgkmcnt(0)
	v_lshlrev_b32_e32 v10, 16, v7
	s_waitcnt vmcnt(7)
	v_lshlrev_b32_e32 v0, 16, v88
	v_lshlrev_b32_e32 v1, 16, v4
	v_mul_f32_e32 v0, v1, v0
	v_and_b32_e32 v1, 0xffff0000, v4
	v_and_b32_e32 v2, 0xffff0000, v88
	v_mul_f32_e32 v1, v1, v2
	v_lshlrev_b32_e32 v2, 16, v89
	v_lshlrev_b32_e32 v3, 16, v5
	v_mul_f32_e32 v2, v3, v2
	v_and_b32_e32 v3, 0xffff0000, v5
	v_and_b32_e32 v4, 0xffff0000, v89
	v_mul_f32_e32 v3, v3, v4
	v_lshlrev_b32_e32 v4, 16, v90
	v_lshlrev_b32_e32 v5, 16, v6
	v_mul_f32_e32 v4, v5, v4
	v_and_b32_e32 v5, 0xffff0000, v6
	v_and_b32_e32 v6, 0xffff0000, v90
	v_mul_f32_e32 v5, v5, v6
	v_lshlrev_b32_e32 v6, 16, v91
	v_mul_f32_e32 v6, v10, v6
	v_and_b32_e32 v7, 0xffff0000, v7
	v_and_b32_e32 v10, 0xffff0000, v91
	v_mul_f32_e32 v7, v7, v10
	v_cvt_pk_bf16_f32 v0, v0, v1
	v_cvt_pk_bf16_f32 v1, v2, v3
	v_cvt_pk_bf16_f32 v2, v4, v5
	v_cvt_pk_bf16_f32 v3, v6, v7
	ds_read_b128 v[4:7], v12 offset:17408
	v_lshl_add_u64 v[10:11], v[8:9], 0, v[108:109]
	global_store_dwordx4 v[10:11], v[0:3], off
	s_waitcnt lgkmcnt(0)
	v_lshlrev_b32_e32 v10, 16, v7
	s_waitcnt vmcnt(7)
	v_lshlrev_b32_e32 v0, 16, v84
	v_lshlrev_b32_e32 v1, 16, v4
	v_mul_f32_e32 v0, v1, v0
	v_and_b32_e32 v1, 0xffff0000, v4
	v_and_b32_e32 v2, 0xffff0000, v84
	v_mul_f32_e32 v1, v1, v2
	v_lshlrev_b32_e32 v2, 16, v85
	v_lshlrev_b32_e32 v3, 16, v5
	v_mul_f32_e32 v2, v3, v2
	v_and_b32_e32 v3, 0xffff0000, v5
	v_and_b32_e32 v4, 0xffff0000, v85
	v_mul_f32_e32 v3, v3, v4
	v_lshlrev_b32_e32 v4, 16, v86
	v_lshlrev_b32_e32 v5, 16, v6
	v_mul_f32_e32 v4, v5, v4
	v_and_b32_e32 v5, 0xffff0000, v6
	v_and_b32_e32 v6, 0xffff0000, v86
	v_mul_f32_e32 v5, v5, v6
	v_lshlrev_b32_e32 v6, 16, v87
	v_mul_f32_e32 v6, v10, v6
	v_and_b32_e32 v7, 0xffff0000, v7
	v_and_b32_e32 v10, 0xffff0000, v87
	v_mul_f32_e32 v7, v7, v10
	v_cvt_pk_bf16_f32 v0, v0, v1
	v_cvt_pk_bf16_f32 v1, v2, v3
	v_cvt_pk_bf16_f32 v2, v4, v5
	v_cvt_pk_bf16_f32 v3, v6, v7
	ds_read_b128 v[4:7], v12 offset:26112
	v_lshl_add_u64 v[10:11], v[8:9], 0, v[106:107]
	global_store_dwordx4 v[10:11], v[0:3], off
	s_waitcnt lgkmcnt(0)
; DI float bflo(unsigned w) { return __uint_as_float(w << 16); }
; DI float bfhi(unsigned w) { return __uint_as_float(w & 0xffff0000u); }
; DI void store8(bf16_t* p, f32x4 a, f32x4 b) { u32x4 w = {cvt_pk_bf16(a[0], a[1]), cvt_pk_bf16(a[2], a[3]), cvt_pk_bf16(b[0], b[1]), cvt_pk_bf16(b[2], b[3])}; *(u32x4*)p = w; }
; DI void attn_dense_body(const bf16_t* __restrict__ Qb, const bf16_t* __restrict__ Kh, const bf16_t* __restrict__ Vh, ...
;     ...
; #pragma unroll
;   for (int it = 0; it < 8; ++it) { const int row = (tid >> 4) + 32 * it, c8 = (tid & 15) * 8;
;     const u32x4 ov = *(const u32x4*)(stg + row * 136 + c8);
;     f32x4 y0, y1;
;     y0[0] = bflo(ov[0]) * bflo(gv[it][0]); y0[1] = bfhi(ov[0]) * bfhi(gv[it][0]); y0[2] = bflo(ov[1]) * bflo(gv[it][1]); y0[3] = bfhi(ov[1]) * bfhi(gv[it][1]);
;     y1[0] = bflo(ov[2]) * bflo(gv[it][2]); y1[1] = bfhi(ov[2]) * bfhi(gv[it][2]); y1[2] = bflo(ov[3]) * bflo(gv[it][3]); y1[3] = bfhi(ov[3]) * bfhi(gv[it][3]);
;     store8(Ob + (long)row * LDQ + c8, y0, y1); }
;     ...
;   __syncthreads();
	v_lshlrev_b32_e32 v10, 16, v7
	s_waitcnt vmcnt(7)
	v_lshlrev_b32_e32 v0, 16, v80
	v_lshlrev_b32_e32 v1, 16, v4
	v_mul_f32_e32 v0, v1, v0
	v_and_b32_e32 v1, 0xffff0000, v4
	v_and_b32_e32 v2, 0xffff0000, v80
	v_mul_f32_e32 v1, v1, v2
	v_lshlrev_b32_e32 v2, 16, v81
	v_lshlrev_b32_e32 v3, 16, v5
	v_mul_f32_e32 v2, v3, v2
	v_and_b32_e32 v3, 0xffff0000, v5
	v_and_b32_e32 v4, 0xffff0000, v81
	v_mul_f32_e32 v3, v3, v4
	v_lshlrev_b32_e32 v4, 16, v82
	v_lshlrev_b32_e32 v5, 16, v6
	v_mul_f32_e32 v4, v5, v4
	v_and_b32_e32 v5, 0xffff0000, v6
	v_and_b32_e32 v6, 0xffff0000, v82
	v_mul_f32_e32 v5, v5, v6
	v_lshlrev_b32_e32 v6, 16, v83
	v_mul_f32_e32 v6, v10, v6
	v_and_b32_e32 v7, 0xffff0000, v7
	v_and_b32_e32 v10, 0xffff0000, v83
	v_mul_f32_e32 v7, v7, v10
	v_cvt_pk_bf16_f32 v0, v0, v1
	v_cvt_pk_bf16_f32 v1, v2, v3
	v_cvt_pk_bf16_f32 v2, v4, v5
	v_cvt_pk_bf16_f32 v3, v6, v7
	ds_read_b128 v[4:7], v12 offset:34816
	v_lshl_add_u64 v[10:11], v[8:9], 0, v[104:105]
	global_store_dwordx4 v[10:11], v[0:3], off
	s_waitcnt lgkmcnt(0)
	v_lshlrev_b32_e32 v10, 16, v7
	s_waitcnt vmcnt(7)
	v_lshlrev_b32_e32 v0, 16, v76
	v_lshlrev_b32_e32 v1, 16, v4
	v_mul_f32_e32 v0, v1, v0
	v_and_b32_e32 v1, 0xffff0000, v4
	v_and_b32_e32 v2, 0xffff0000, v76
	v_mul_f32_e32 v1, v1, v2
	v_lshlrev_b32_e32 v2, 16, v77
	v_lshlrev_b32_e32 v3, 16, v5
	v_mul_f32_e32 v2, v3, v2
	v_and_b32_e32 v3, 0xffff0000, v5
	v_and_b32_e32 v4, 0xffff0000, v77
	v_mul_f32_e32 v3, v3, v4
	v_lshlrev_b32_e32 v4, 16, v78
	v_lshlrev_b32_e32 v5, 16, v6
	v_mul_f32_e32 v4, v5, v4
	v_and_b32_e32 v5, 0xffff0000, v6
	v_and_b32_e32 v6, 0xffff0000, v78
	v_mul_f32_e32 v5, v5, v6
	v_lshlrev_b32_e32 v6, 16, v79
	v_mul_f32_e32 v6, v10, v6
	v_and_b32_e32 v7, 0xffff0000, v7
	v_and_b32_e32 v10, 0xffff0000, v79
	v_mul_f32_e32 v7, v7, v10
	v_cvt_pk_bf16_f32 v0, v0, v1
	v_cvt_pk_bf16_f32 v1, v2, v3
	v_cvt_pk_bf16_f32 v2, v4, v5
	v_cvt_pk_bf16_f32 v3, v6, v7
	ds_read_b128 v[4:7], v12 offset:43520
	v_lshl_add_u64 v[10:11], v[8:9], 0, v[102:103]
	global_store_dwordx4 v[10:11], v[0:3], off
	s_waitcnt lgkmcnt(0)
	v_lshlrev_b32_e32 v10, 16, v7
	s_waitcnt vmcnt(7)
	v_lshlrev_b32_e32 v0, 16, v72
	v_lshlrev_b32_e32 v1, 16, v4
	v_mul_f32_e32 v0, v1, v0
	v_and_b32_e32 v1, 0xffff0000, v4
	v_and_b32_e32 v2, 0xffff0000, v72
	v_mul_f32_e32 v1, v1, v2
	v_lshlrev_b32_e32 v2, 16, v73
	v_lshlrev_b32_e32 v3, 16, v5
	v_mul_f32_e32 v2, v3, v2
	v_and_b32_e32 v3, 0xffff0000, v5
	v_and_b32_e32 v4, 0xffff0000, v73
	v_mul_f32_e32 v3, v3, v4
	v_lshlrev_b32_e32 v4, 16, v74
	v_lshlrev_b32_e32 v5, 16, v6
	v_mul_f32_e32 v4, v5, v4
	v_and_b32_e32 v5, 0xffff0000, v6
	v_and_b32_e32 v6, 0xffff0000, v74
	v_mul_f32_e32 v5, v5, v6
	v_lshlrev_b32_e32 v6, 16, v75
	v_mul_f32_e32 v6, v10, v6
	v_and_b32_e32 v7, 0xffff0000, v7
	v_and_b32_e32 v10, 0xffff0000, v75
	v_mul_f32_e32 v7, v7, v10
	v_cvt_pk_bf16_f32 v0, v0, v1
	v_cvt_pk_bf16_f32 v1, v2, v3
	v_cvt_pk_bf16_f32 v2, v4, v5
	v_cvt_pk_bf16_f32 v3, v6, v7
	ds_read_b128 v[4:7], v12 offset:52224
	v_lshl_add_u64 v[10:11], v[8:9], 0, v[100:101]
	global_store_dwordx4 v[10:11], v[0:3], off
	s_waitcnt lgkmcnt(0)
	v_lshlrev_b32_e32 v10, 16, v7
	s_waitcnt vmcnt(7)
	v_lshlrev_b32_e32 v0, 16, v68
	v_lshlrev_b32_e32 v1, 16, v4
	v_mul_f32_e32 v0, v1, v0
	v_and_b32_e32 v1, 0xffff0000, v4
	v_and_b32_e32 v2, 0xffff0000, v68
	v_mul_f32_e32 v1, v1, v2
	v_lshlrev_b32_e32 v2, 16, v69
	v_lshlrev_b32_e32 v3, 16, v5
	v_mul_f32_e32 v2, v3, v2
	v_and_b32_e32 v3, 0xffff0000, v5
	v_and_b32_e32 v4, 0xffff0000, v69
	v_mul_f32_e32 v3, v3, v4
	v_lshlrev_b32_e32 v4, 16, v70
	v_lshlrev_b32_e32 v5, 16, v6
	v_mul_f32_e32 v4, v5, v4
	v_and_b32_e32 v5, 0xffff0000, v6
	v_and_b32_e32 v6, 0xffff0000, v70
	v_mul_f32_e32 v5, v5, v6
	v_lshlrev_b32_e32 v6, 16, v71
	v_mul_f32_e32 v6, v10, v6
	v_and_b32_e32 v7, 0xffff0000, v7
	v_and_b32_e32 v10, 0xffff0000, v71
	v_mul_f32_e32 v7, v7, v10
	v_cvt_pk_bf16_f32 v0, v0, v1
	v_cvt_pk_bf16_f32 v1, v2, v3
	v_cvt_pk_bf16_f32 v2, v4, v5
	v_cvt_pk_bf16_f32 v3, v6, v7
	ds_read_b128 v[4:7], v12 offset:60928
	v_lshl_add_u64 v[10:11], v[8:9], 0, v[98:99]
	global_store_dwordx4 v[10:11], v[0:3], off
	s_waitcnt vmcnt(7)
	s_nop 0
	v_lshlrev_b32_e32 v0, 16, v64
	s_waitcnt lgkmcnt(0)
	v_lshlrev_b32_e32 v1, 16, v4
	v_mul_f32_e32 v0, v1, v0
	v_and_b32_e32 v1, 0xffff0000, v4
	v_and_b32_e32 v2, 0xffff0000, v64
	v_mul_f32_e32 v1, v1, v2
	v_lshlrev_b32_e32 v2, 16, v65
	v_lshlrev_b32_e32 v3, 16, v5
	v_mul_f32_e32 v2, v3, v2
	v_and_b32_e32 v3, 0xffff0000, v5
	v_and_b32_e32 v4, 0xffff0000, v65
	v_mul_f32_e32 v3, v3, v4
	v_lshlrev_b32_e32 v4, 16, v66
	v_lshlrev_b32_e32 v5, 16, v6
	v_mul_f32_e32 v10, v5, v4
	v_and_b32_e32 v4, 0xffff0000, v6
	v_and_b32_e32 v5, 0xffff0000, v66
	v_mul_f32_e32 v6, v4, v5
	v_lshlrev_b32_e32 v4, 16, v67
	v_lshlrev_b32_e32 v5, 16, v7
	v_mul_f32_e32 v11, v5, v4
	v_and_b32_e32 v4, 0xffff0000, v7
	v_and_b32_e32 v5, 0xffff0000, v67
	v_mul_f32_e32 v7, v4, v5
	v_lshl_add_u64 v[4:5], v[8:9], 0, v[96:97]
	v_cvt_pk_bf16_f32 v0, v0, v1
	v_cvt_pk_bf16_f32 v1, v2, v3
	v_cvt_pk_bf16_f32 v2, v10, v6
	v_cvt_pk_bf16_f32 v3, v11, v7
	global_store_dwordx4 v[4:5], v[0:3], off
	s_barrier
	s_cbranch_scc0 .LBB0_853

; DI float bflo(unsigned w) { return __uint_as_float(w << 16); }
; DI float bfhi(unsigned w) { return __uint_as_float(w & 0xffff0000u); }
; DI void attn_dense_body(const bf16_t* __restrict__ Qb, const bf16_t* __restrict__ Kh, const bf16_t* __restrict__ Vh, ...
;     ...
;   const bf16_t* Qw = Qb + (long)(wid * QBLK + r32) * LDQ + hi * 8;
; #pragma unroll
;   for (int d0 = 0; d0 < 8; ++d0) qr[d0] = ld8(Qw + d0 * 16);
;   {
;     float xf[8][8]; float ss = 0.f;
; #pragma unroll
;     for (int d0 = 0; d0 < 8; ++d0) { const u32x4 w = *reinterpret_cast<const u32x4*>(&qr[d0]);
; #pragma unroll
;       for (int i = 0; i < 4; ++i) { xf[d0][2 * i] = bflo(w[i]); xf[d0][2 * i + 1] = bfhi(w[i]); ss += xf[d0][2 * i] * xf[d0][2 * i] + xf[d0][2 * i + 1] * xf[d0][2 * i + 1]; } }
;     { auto rr = __builtin_amdgcn_permlane32_swap(__float_as_uint(ss), __float_as_uint(ss), false, false); ss = __uint_as_float(rr[0]) + __uint_as_float(rr[1]); }
.LBB0_831:
	s_ashr_i32 s11, s10, 31
	s_lshl_b64 s[8:9], s[10:11], 10
	s_lshl_b32 s11, s13, 7
	s_add_u32 s8, s8, s11
	v_mov_b32_e32 v160, v252
	s_addc_u32 s9, s9, 0
	s_movk_i32 s11, 0xffe0
	s_waitcnt vmcnt(9)
	v_ashrrev_i32_e32 v34, 1, v160
	s_lshl_b64 s[8:9], s[8:9], 1
	v_bfi_b32 v8, s11, v34, v160
	s_add_u32 s16, s52, s8
	v_ashrrev_i32_e32 v9, 31, v8
	s_addc_u32 s17, s53, s9
	v_bfe_u32 v179, v160, 5, 1
	v_lshlrev_b64 v[8:9], 11, v[8:9]
	v_lshl_add_u64 v[12:13], s[16:17], 0, v[8:9]
	v_lshlrev_b32_e32 v180, 4, v179
	v_and_b32_e32 v161, 32, v160
	s_waitcnt vmcnt(4)
	v_lshl_add_u64 v[32:33], v[12:13], 0, v[180:181]
	global_load_dwordx4 v[16:19], v161, s[6:7] offset:64
	global_load_dwordx4 v[20:23], v161, s[6:7] offset:80
	global_load_dwordx4 v[0:3], v161, s[6:7] offset:192
	global_load_dwordx4 v[4:7], v161, s[6:7] offset:208
	global_load_dwordx4 v[24:27], v161, s[6:7] offset:16
	global_load_dwordx4 v[8:11], v161, s[6:7] offset:144
	global_load_dwordx4 v[56:59], v[32:33], off offset:96 nt
	global_load_dwordx4 v[72:75], v[32:33], off offset:32 nt
	global_load_dwordx4 v[76:79], v[32:33], off offset:64 nt
	global_load_dwordx4 v[80:83], v[32:33], off nt
	global_load_dwordx4 v[28:31], v161, s[6:7]
	global_load_dwordx4 v[12:15], v161, s[6:7] offset:128
	v_and_b32_e32 v197, 0xffffffe0, v34
	global_load_dwordx4 v[44:47], v[32:33], off offset:128 nt
	global_load_dwordx4 v[36:39], v[32:33], off offset:160 nt
	global_load_dwordx4 v[40:43], v[32:33], off offset:192 nt
	s_nop 0
	global_load_dwordx4 v[32:35], v[32:33], off offset:224 nt
	v_and_b32_e32 v196, 31, v160
	s_waitcnt vmcnt(15)
	v_mov_b32_e32 v68, v16
	v_mov_b32_e32 v66, v18
	s_waitcnt vmcnt(9)
	v_and_b32_e32 v95, 0xffff0000, v56
	v_and_b32_e32 v61, 0xffff0000, v59
	s_waitcnt vmcnt(7)
	v_and_b32_e32 v111, 0xffff0000, v77
	s_waitcnt vmcnt(6)
	v_and_b32_e32 v109, 0xffff0000, v81
	v_lshlrev_b32_e32 v110, 16, v81
	v_mul_f32_e32 v116, v109, v109
	v_lshlrev_b32_e32 v48, 16, v59
	v_and_b32_e32 v93, 0xffff0000, v57
	v_lshlrev_b32_e32 v52, 16, v57
	v_and_b32_e32 v57, 0xffff0000, v72
	v_lshlrev_b32_e32 v56, 16, v56
	v_and_b32_e32 v59, 0xffff0000, v83
	v_mul_f32_e32 v100, v95, v95
	v_lshlrev_b32_e32 v108, 16, v77
	v_pk_fma_f32 v[120:121], v[110:111], v[110:111], v[116:117] op_sel_hi:[1,1,0]
	v_mul_f32_e32 v116, v111, v111
	v_and_b32_e32 v119, 0xffff0000, v80
	v_and_b32_e32 v97, 0xffff0000, v79
	v_lshlrev_b32_e32 v96, 16, v83
	v_mul_f32_e32 v102, v59, v59
	v_pk_fma_f32 v[106:107], v[56:57], v[56:57], v[100:101] op_sel_hi:[1,1,0]
	v_and_b32_e32 v101, 0xffff0000, v82
	v_pk_fma_f32 v[122:123], v[108:109], v[108:109], v[116:117] op_sel_hi:[1,1,0]
	v_and_b32_e32 v117, 0xffff0000, v76
	v_lshlrev_b32_e32 v116, 16, v80
	v_lshlrev_b32_e32 v118, 16, v76
	v_mul_f32_e32 v76, v119, v119
	v_pk_fma_f32 v[112:113], v[96:97], v[96:97], v[102:103] op_sel_hi:[1,1,0]
	v_and_b32_e32 v103, 0xffff0000, v78
	v_lshlrev_b32_e32 v102, 16, v82
	v_lshlrev_b32_e32 v100, 16, v78
	v_mul_f32_e32 v78, v101, v101
	v_pk_fma_f32 v[76:77], v[116:117], v[116:117], v[76:77] op_sel_hi:[1,1,0]
	v_and_b32_e32 v63, 0xffff0000, v58
	v_lshlrev_b32_e32 v50, 16, v58
	v_lshlrev_b32_e32 v58, 16, v79
	v_pk_fma_f32 v[78:79], v[102:103], v[102:103], v[78:79] op_sel_hi:[1,1,0]
	v_pk_add_f32 v[76:77], v[76:77], v[120:121]
	v_and_b32_e32 v53, 0xffff0000, v73
	v_lshlrev_b32_e32 v94, 16, v72
	v_mul_f32_e32 v98, v57, v57
	v_pk_add_f32 v[76:77], v[78:79], v[76:77]
	v_and_b32_e32 v51, 0xffff0000, v74
	v_lshlrev_b32_e32 v92, 16, v73
	v_mul_f32_e32 v88, v53, v53
	v_pk_fma_f32 v[98:99], v[94:95], v[94:95], v[98:99] op_sel_hi:[1,1,0]
	v_pk_add_f32 v[76:77], v[112:113], v[76:77]
	v_and_b32_e32 v49, 0xffff0000, v75
	v_lshlrev_b32_e32 v62, 16, v74
	v_mul_f32_e32 v84, v51, v51
	v_pk_fma_f32 v[88:89], v[92:93], v[92:93], v[88:89] op_sel_hi:[1,1,0]
	v_pk_add_f32 v[76:77], v[98:99], v[76:77]
	v_lshlrev_b32_e32 v60, 16, v75
	v_mul_f32_e32 v72, v49, v49
	v_pk_fma_f32 v[84:85], v[62:63], v[62:63], v[84:85] op_sel_hi:[1,1,0]
	v_pk_add_f32 v[76:77], v[88:89], v[76:77]
	v_pk_fma_f32 v[72:73], v[60:61], v[60:61], v[72:73] op_sel_hi:[1,1,0]
	v_mul_f32_e32 v80, v117, v117
	v_pk_add_f32 v[76:77], v[84:85], v[76:77]
	v_pk_fma_f32 v[80:81], v[118:119], v[118:119], v[80:81] op_sel_hi:[1,1,0]
	v_pk_add_f32 v[72:73], v[72:73], v[76:77]
	v_mul_f32_e32 v82, v103, v103
	v_pk_add_f32 v[72:73], v[80:81], v[72:73]
	v_mul_f32_e32 v104, v97, v97
	v_pk_fma_f32 v[82:83], v[100:101], v[100:101], v[82:83] op_sel_hi:[1,1,0]
	v_pk_add_f32 v[72:73], v[122:123], v[72:73]
	v_pk_fma_f32 v[104:105], v[58:59], v[58:59], v[104:105] op_sel_hi:[1,1,0]
	v_pk_add_f32 v[72:73], v[82:83], v[72:73]
	v_mul_f32_e32 v90, v93, v93
	v_pk_add_f32 v[72:73], v[104:105], v[72:73]
	v_mul_f32_e32 v86, v63, v63
	v_pk_fma_f32 v[90:91], v[52:53], v[52:53], v[90:91] op_sel_hi:[1,1,0]
	v_pk_add_f32 v[72:73], v[106:107], v[72:73]
	v_mul_f32_e32 v74, v61, v61
	v_pk_fma_f32 v[86:87], v[50:51], v[50:51], v[86:87] op_sel_hi:[1,1,0]
	v_pk_add_f32 v[72:73], v[90:91], v[72:73]
	v_pk_fma_f32 v[74:75], v[48:49], v[48:49], v[74:75] op_sel_hi:[1,1,0]
	v_pk_add_f32 v[72:73], v[86:87], v[72:73]
	s_waitcnt vmcnt(1)
; DI float bflo(unsigned w) { return __uint_as_float(w << 16); }
; DI float bfhi(unsigned w) { return __uint_as_float(w & 0xffff0000u); }
; DI void attn_dense_body(const bf16_t* __restrict__ Qb, const bf16_t* __restrict__ Kh, const bf16_t* __restrict__ Vh, ...
;     ...
;     for (int d0 = 0; d0 < 8; ++d0) { const u32x4 w = *reinterpret_cast<const u32x4*>(&qr[d0]);
; #pragma unroll
;       for (int i = 0; i < 4; ++i) { xf[d0][2 * i] = bflo(w[i]); xf[d0][2 * i + 1] = bfhi(w[i]); ss += xf[d0][2 * i] * xf[d0][2 * i] + xf[d0][2 * i + 1] * xf[d0][2 * i + 1]; } }
;     { auto rr = __builtin_amdgcn_permlane32_swap(__float_as_uint(ss), __float_as_uint(ss), false, false); ss = __uint_as_float(rr[0]) + __uint_as_float(rr[1]); }
;     const float rinv = rsqrtf(ss * (1.f / 128.f) + 1e-6f);
; #pragma unroll
;     for (int d0 = 0; d0 < 8; ++d0) { const f32x4 s0 = *(const f32x4*)(qsc + d0 * 16 + hi * 8), s1 = *(const f32x4*)(qsc + d0 * 16 + hi * 8 + 4);
; #pragma unroll
;       for (int e = 0; e < 4; ++e) { xf[d0][e] *= rinv * s0[e]; xf[d0][4 + e] *= rinv * s1[e]; } }
	v_and_b32_e32 v149, 0xffff0000, v40
	v_pk_add_f32 v[72:73], v[74:75], v[72:73]
	v_and_b32_e32 v75, 0xffff0000, v44
	v_lshlrev_b32_e32 v74, 16, v44
	v_mul_f32_e32 v44, v75, v75
	v_lshlrev_b32_e32 v148, 16, v40
	v_mul_f32_e32 v40, v149, v149
	v_and_b32_e32 v151, 0xffff0000, v45
	v_pk_fma_f32 v[76:77], v[74:75], v[74:75], v[44:45] op_sel_hi:[1,1,0]
	v_pk_fma_f32 v[78:79], v[148:149], v[148:149], v[40:41] op_sel_hi:[1,1,0]
	v_lshlrev_b32_e32 v150, 16, v45
	v_mul_f32_e32 v40, v151, v151
	v_and_b32_e32 v153, 0xffff0000, v41
	v_pk_add_f32 v[72:73], v[76:77], v[72:73]
	v_pk_fma_f32 v[44:45], v[150:151], v[150:151], v[40:41] op_sel_hi:[1,1,0]
	v_lshlrev_b32_e32 v152, 16, v41
	v_mul_f32_e32 v40, v153, v153
	v_and_b32_e32 v155, 0xffff0000, v46
	v_pk_fma_f32 v[76:77], v[152:153], v[152:153], v[40:41] op_sel_hi:[1,1,0]
	v_pk_add_f32 v[40:41], v[44:45], v[72:73]
	v_lshlrev_b32_e32 v154, 16, v46
	v_mul_f32_e32 v44, v155, v155
	v_and_b32_e32 v157, 0xffff0000, v42
	v_and_b32_e32 v159, 0xffff0000, v47
	v_and_b32_e32 v163, 0xffff0000, v43
	global_load_dwordx4 v[122:125], v161, s[6:7] offset:272
	global_load_dwordx4 v[126:129], v161, s[6:7] offset:256
	global_load_dwordx4 v[130:133], v161, s[6:7] offset:336
	global_load_dwordx4 v[134:137], v161, s[6:7] offset:320
	global_load_dwordx4 v[138:141], v161, s[6:7] offset:400
	global_load_dwordx4 v[142:145], v161, s[6:7] offset:384
	v_pk_fma_f32 v[44:45], v[154:155], v[154:155], v[44:45] op_sel_hi:[1,1,0]
	v_lshlrev_b32_e32 v156, 16, v42
	v_lshlrev_b32_e32 v158, 16, v47
	v_mul_f32_e32 v42, v159, v159
	v_lshlrev_b32_e32 v162, 16, v43
	v_mov_b32_e32 v46, v163
	v_mov_b32_e32 v47, v157
	v_pk_add_f32 v[40:41], v[44:45], v[40:41]
	v_pk_fma_f32 v[44:45], v[158:159], v[158:159], v[42:43] op_sel_hi:[1,1,0]
	v_mov_b32_e32 v42, v162
	v_mov_b32_e32 v43, v156
	v_pk_mul_f32 v[46:47], v[46:47], v[46:47]
	v_pk_add_f32 v[80:81], v[44:45], v[40:41]
	v_pk_fma_f32 v[72:73], v[42:43], v[42:43], v[46:47]
	global_load_dwordx4 v[40:43], v161, s[6:7] offset:464
	global_load_dwordx4 v[44:47], v161, s[6:7] offset:448
	v_and_b32_e32 v165, 0xffff0000, v36
	v_lshlrev_b32_e32 v164, 16, v36
	v_mul_f32_e32 v36, v165, v165
	v_pk_fma_f32 v[82:83], v[164:165], v[164:165], v[36:37] op_sel_hi:[1,1,0]
	v_lshlrev_b32_e32 v36, 16, v37
	v_and_b32_e32 v37, 0xffff0000, v37
	s_waitcnt vmcnt(8)
	v_lshlrev_b32_e32 v166, 16, v32
	v_and_b32_e32 v167, 0xffff0000, v32
	v_mul_f32_e32 v32, v37, v37
	v_and_b32_e32 v171, 0xffff0000, v38
	v_pk_add_f32 v[80:81], v[82:83], v[80:81]
	v_pk_fma_f32 v[82:83], v[36:37], v[36:37], v[32:33] op_sel_hi:[1,1,0]
	v_lshlrev_b32_e32 v170, 16, v38
	v_mul_f32_e32 v38, v171, v171
	v_and_b32_e32 v175, 0xffff0000, v39
	v_pk_add_f32 v[80:81], v[82:83], v[80:81]
	v_pk_fma_f32 v[82:83], v[170:171], v[170:171], v[38:39] op_sel_hi:[1,1,0]
	v_lshlrev_b32_e32 v172, 16, v34
	v_and_b32_e32 v173, 0xffff0000, v34
	v_lshlrev_b32_e32 v174, 16, v39
	v_mul_f32_e32 v34, v175, v175
	v_pk_add_f32 v[80:81], v[82:83], v[80:81]
	v_pk_fma_f32 v[38:39], v[174:175], v[174:175], v[34:35] op_sel_hi:[1,1,0]
	v_and_b32_e32 v169, 0xffff0000, v33
	v_pk_add_f32 v[38:39], v[38:39], v[80:81]
	v_lshlrev_b32_e32 v168, 16, v33
	v_pk_add_f32 v[38:39], v[78:79], v[38:39]
	v_mov_b32_e32 v84, v169
	v_mov_b32_e32 v85, v167
	v_pk_add_f32 v[38:39], v[76:77], v[38:39]
	v_mov_b32_e32 v32, v168
	v_mov_b32_e32 v33, v166
	v_pk_mul_f32 v[84:85], v[84:85], v[84:85]
	v_and_b32_e32 v177, 0xffff0000, v35
	v_pk_add_f32 v[38:39], v[72:73], v[38:39] op_sel:[1,0] op_sel_hi:[0,1]
	v_pk_fma_f32 v[32:33], v[32:33], v[32:33], v[84:85]
	v_lshlrev_b32_e32 v176, 16, v35
	v_mov_b32_e32 v82, v177
	v_mov_b32_e32 v83, v173
	v_pk_add_f32 v[38:39], v[72:73], v[38:39]
	v_mov_b32_e32 v34, v176
	v_mov_b32_e32 v35, v172
	v_pk_mul_f32 v[82:83], v[82:83], v[82:83]
	v_pk_add_f32 v[38:39], v[32:33], v[38:39] op_sel:[1,0] op_sel_hi:[0,1]
	v_pk_fma_f32 v[34:35], v[34:35], v[34:35], v[82:83]
	v_pk_add_f32 v[32:33], v[32:33], v[38:39]
	v_mov_b32_e32 v16, v0
	v_pk_add_f32 v[32:33], v[34:35], v[32:33] op_sel:[1,0] op_sel_hi:[0,1]
	v_pk_add_f32 v[32:33], v[34:35], v[32:33]
	v_mov_b32_e32 v67, v3
	v_mov_b32_e32 v33, v32
	s_nop 1
	v_permlane32_swap_b32_e32 v32, v33
	v_add_f32_e32 v32, v32, v33
	v_fmamk_f32 v32, v32, 0x3c000000, v183
	v_mul_f32_e32 v33, 0x4b800000, v32
	v_cmp_gt_f32_e32 vcc, s94, v32
	v_mov_b32_e32 v64, v20
	v_mov_b32_e32 v65, v5
	v_cndmask_b32_e32 v32, v32, v33, vcc
	v_rsq_f32_e32 v34, v32
	v_mov_b32_e32 v18, v2
	v_mov_b32_e32 v146, v30
	v_mov_b32_e32 v147, v15
	v_mul_f32_e32 v35, 0x45800000, v34
	v_cndmask_b32_e32 v120, v34, v35, vcc
	v_pk_mul_f32 v[16:17], v[16:17], v[120:121] op_sel_hi:[1,0]
	v_pk_mul_f32 v[76:77], v[66:67], v[120:121] op_sel_hi:[1,0]
	v_pk_mul_f32 v[66:67], v[16:17], v[56:57]
	s_waitcnt vmcnt(6)
	v_pk_mul_f32 v[16:17], v[120:121], v[126:127] op_sel_hi:[0,1]
	v_pk_mul_f32 v[86:87], v[76:77], v[92:93]
	v_pk_mul_f32 v[76:77], v[16:17], v[74:75]
	v_pk_mul_f32 v[16:17], v[120:121], v[128:129] op_sel_hi:[0,1]
	v_mov_b32_e32 v70, v26
	v_mov_b32_e32 v71, v11
	v_pk_mul_f32 v[38:39], v[146:147], v[120:121] op_sel_hi:[1,0]
	v_pk_mul_f32 v[72:73], v[64:65], v[120:121] op_sel_hi:[1,0]
	v_pk_mul_f32 v[18:19], v[18:19], v[120:121] op_sel_hi:[1,0]
	v_pk_mul_f32 v[74:75], v[16:17], v[150:151]
	s_waitcnt vmcnt(4)
; DI void attn_dense_body(const bf16_t* __restrict__ Qb, const bf16_t* __restrict__ Kh, const bf16_t* __restrict__ Vh, ...
;     ...
;     for (int d0 = 0; d0 < 8; ++d0) { const f32x4 s0 = *(const f32x4*)(qsc + d0 * 16 + hi * 8), s1 = *(const f32x4*)(qsc + d0 * 16 + hi * 8 + 4);
; #pragma unroll
;       for (int e = 0; e < 4; ++e) { xf[d0][e] *= rinv * s0[e]; xf[d0][4 + e] *= rinv * s1[e]; } }
;     if (rope_t0 >= 0) { const int t = rope_t0 + wid * QBLK + r32;
; #pragma unroll
;       for (int half = 0; half < 2; ++half) { const int pos = half ? (t & 63) : (t >> 6);
; #pragma unroll
;         for (int dp = 0; dp < 2; ++dp) { const f32x4* cp = (const f32x4*)(ropeA + pos * 32 + dp * 16 + hi * 8);
; #pragma unroll
;           for (int e2 = 0; e2 < 4; ++e2) { const f32x4 cs = cp[e2];
;             const int da = half * 4 + dp, db = da + 2;
;             float x1 = xf[da][2 * e2], x2 = xf[db][2 * e2]; xf[da][2 * e2] = x1 * cs[0] - x2 * cs[1]; xf[db][2 * e2] = x1 * cs[1] + x2 * cs[0];
;             x1 = xf[da][2 * e2 + 1]; x2 = xf[db][2 * e2 + 1]; xf[da][2 * e2 + 1] = x1 * cs[2] - x2 * cs[3]; xf[db][2 * e2 + 1] = x1 * cs[3] + x2 * cs[2]; } } } }
	v_pk_mul_f32 v[16:17], v[120:121], v[134:135] op_sel_hi:[0,1]
	v_mov_b32_e32 v69, v1
	v_mov_b32_e32 v32, v28
	v_mov_b32_e32 v28, v12
	v_pk_mul_f32 v[70:71], v[70:71], v[120:121] op_sel_hi:[1,0]
	v_pk_mul_f32 v[106:107], v[38:39], v[110:111]
	v_pk_mul_f32 v[84:85], v[72:73], v[62:63]
	v_pk_mul_f32 v[72:73], v[18:19], v[52:53]
	v_pk_mul_f32 v[18:19], v[120:121], v[122:123] op_sel_hi:[0,1]
	v_pk_mul_f32 v[38:39], v[16:17], v[164:165]
	v_pk_mul_f32 v[16:17], v[120:121], v[136:137] op_sel_hi:[0,1]
	v_mov_b32_e32 v114, v24
	v_mov_b32_e32 v115, v9
	v_mov_b32_e32 v24, v8
	v_mov_b32_e32 v30, v14
	v_pk_mul_f32 v[28:29], v[28:29], v[120:121] op_sel_hi:[1,0]
	v_pk_mul_f32 v[68:69], v[68:69], v[120:121] op_sel_hi:[1,0]
	v_pk_mul_f32 v[90:91], v[70:71], v[96:97]
	v_pk_mul_f32 v[70:71], v[18:19], v[154:155]
	v_pk_mul_f32 v[18:19], v[120:121], v[124:125] op_sel_hi:[0,1]
	v_pk_mul_f32 v[36:37], v[16:17], v[36:37]
	s_waitcnt vmcnt(2)
	v_pk_mul_f32 v[16:17], v[120:121], v[142:143] op_sel_hi:[0,1]
	v_mov_b32_e32 v54, v22
	v_mov_b32_e32 v55, v7
	v_mov_b32_e32 v22, v6
	v_mov_b32_e32 v20, v4
	v_mov_b32_e32 v33, v13
	v_pk_mul_f32 v[34:35], v[114:115], v[120:121] op_sel_hi:[1,0]
	v_pk_mul_f32 v[24:25], v[24:25], v[120:121] op_sel_hi:[1,0]
	v_pk_mul_f32 v[30:31], v[30:31], v[120:121] op_sel_hi:[1,0]
	v_pk_mul_f32 v[112:113], v[28:29], v[118:119]
	v_pk_mul_f32 v[88:89], v[68:69], v[94:95]
	v_pk_mul_f32 v[68:69], v[18:19], v[158:159]
	v_pk_mul_f32 v[18:19], v[120:121], v[130:131] op_sel_hi:[0,1]
	v_pk_mul_f32 v[28:29], v[16:17], v[148:149]
	v_pk_mul_f32 v[16:17], v[120:121], v[144:145] op_sel_hi:[0,1]
	v_mov_b32_e32 v26, v10
	v_pk_mul_f32 v[32:33], v[32:33], v[120:121] op_sel_hi:[1,0]
	v_pk_mul_f32 v[20:21], v[20:21], v[120:121] op_sel_hi:[1,0]
	v_pk_mul_f32 v[82:83], v[54:55], v[120:121] op_sel_hi:[1,0]
	v_pk_mul_f32 v[22:23], v[22:23], v[120:121] op_sel_hi:[1,0]
	v_pk_mul_f32 v[54:55], v[24:25], v[100:101]
	v_pk_mul_f32 v[98:99], v[34:35], v[102:103]
	v_pk_mul_f32 v[104:105], v[30:31], v[108:109]
	v_pk_mul_f32 v[34:35], v[18:19], v[170:171]
	v_pk_mul_f32 v[18:19], v[120:121], v[132:133] op_sel_hi:[0,1]
	v_pk_mul_f32 v[30:31], v[16:17], v[152:153]
	s_waitcnt vmcnt(0)
	v_pk_mul_f32 v[16:17], v[120:121], v[44:45] op_sel_hi:[0,1]
	v_pk_mul_f32 v[24:25], v[120:121], v[40:41] op_sel_hi:[0,1]
	v_pk_mul_f32 v[26:27], v[26:27], v[120:121] op_sel_hi:[1,0]
	v_pk_mul_f32 v[114:115], v[32:33], v[116:117]
	v_pk_mul_f32 v[78:79], v[20:21], v[50:51]
	v_pk_mul_f32 v[80:81], v[22:23], v[48:49]
	v_pk_mul_f32 v[32:33], v[18:19], v[174:175]
	v_pk_mul_f32 v[18:19], v[120:121], v[138:139] op_sel_hi:[0,1]
	v_pk_mul_f32 v[20:21], v[120:121], v[140:141] op_sel_hi:[0,1]
	v_pk_mul_f32 v[22:23], v[16:17], v[166:167]
	v_pk_mul_f32 v[16:17], v[24:25], v[172:173]
	v_pk_mul_f32 v[24:25], v[120:121], v[46:47] op_sel_hi:[0,1]
	v_pk_mul_f32 v[40:41], v[120:121], v[42:43] op_sel_hi:[0,1]
	v_pk_mul_f32 v[64:65], v[26:27], v[58:59]
	v_pk_mul_f32 v[82:83], v[82:83], v[60:61]
	v_pk_mul_f32 v[18:19], v[18:19], v[156:157]
	v_pk_mul_f32 v[20:21], v[20:21], v[162:163]
	v_pk_mul_f32 v[26:27], v[24:25], v[168:169]
	s_andn2_b64 vcc, exec, s[4:5]
	v_pk_mul_f32 v[24:25], v[40:41], v[176:177]
	s_cbranch_vccnz .LBB0_833
	s_and_b32 s4, s10, 0xfff
	v_lshlrev_b32_e32 v0, 3, v179
	v_add3_u32 v96, v196, s4, v197
	v_readlane_b32 s4, v253, 9
	v_lshlrev_b32_e32 v0, 3, v0
	v_mov_b32_e32 v1, v181
	v_readlane_b32 s5, v253, 10
	v_pk_mov_b32 v[92:93], v[114:115], v[112:113] op_sel:[1,0]
	v_pk_mov_b32 v[48:49], v[112:113], v[114:115] op_sel:[1,0]
	v_lshl_add_u64 v[12:13], s[4:5], 0, v[0:1]
	v_ashrrev_i32_e32 v0, 1, v96
	v_and_b32_e32 v0, 0xffffffe0, v0
	v_ashrrev_i32_e32 v1, 31, v0
	v_lshl_add_u64 v[62:63], v[0:1], 3, v[12:13]
	global_load_dwordx4 v[0:3], v[62:63], off offset:48
	global_load_dwordx4 v[4:7], v[62:63], off offset:32
	global_load_dwordx4 v[8:11], v[62:63], off offset:16
	global_load_dwordx4 v[40:43], v[62:63], off
	v_pk_mov_b32 v[50:51], v[104:105], v[106:107] op_sel:[1,0]
	v_pk_mov_b32 v[44:45], v[54:55], v[98:99] op_sel:[1,0]
	v_pk_mov_b32 v[46:47], v[64:65], v[90:91] op_sel:[1,0]
	v_pk_mov_b32 v[56:57], v[66:67], v[88:89] op_sel:[1,0]
	v_pk_mov_b32 v[58:59], v[72:73], v[86:87] op_sel:[1,0]
	v_pk_mov_b32 v[60:61], v[78:79], v[84:85] op_sel:[1,0]
	v_pk_mov_b32 v[14:15], v[80:81], v[82:83] op_sel:[1,0]
	s_waitcnt vmcnt(0)
	v_mov_b32_e32 v94, v43
	v_mov_b32_e32 v95, v41
	v_mov_b32_e32 v52, v42
	v_mov_b32_e32 v53, v40
	v_pk_mul_f32 v[92:93], v[92:93], v[94:95]
	s_nop 0
	v_pk_fma_f32 v[48:49], v[48:49], v[52:53], v[92:93] neg_lo:[0,0,1] neg_hi:[0,0,1]
	v_mov_b32_e32 v52, v40
	v_mov_b32_e32 v53, v43
	v_pk_mul_f32 v[52:53], v[112:113], v[52:53]
	v_mov_b32_e32 v40, v41
	v_mov_b32_e32 v41, v42
	v_pk_fma_f32 v[40:41], v[114:115], v[40:41], v[52:53]
	v_pk_mov_b32 v[52:53], v[106:107], v[104:105] op_sel:[1,0]
	v_mov_b32_e32 v92, v11
	v_mov_b32_e32 v93, v9
	v_mov_b32_e32 v42, v10
	v_mov_b32_e32 v43, v8
	v_pk_mul_f32 v[52:53], v[52:53], v[92:93]
	v_mov_b32_e32 v113, v48
	v_pk_fma_f32 v[50:51], v[50:51], v[42:43], v[52:53] neg_lo:[0,0,1] neg_hi:[0,0,1]
	v_mov_b32_e32 v42, v8
	v_mov_b32_e32 v43, v11
	v_pk_mul_f32 v[42:43], v[104:105], v[42:43]
	v_mov_b32_e32 v8, v9
	v_mov_b32_e32 v9, v10
	v_pk_mov_b32 v[10:11], v[98:99], v[54:55] op_sel:[1,0]
	v_mov_b32_e32 v52, v7
	v_mov_b32_e32 v53, v5
	v_pk_fma_f32 v[42:43], v[106:107], v[8:9], v[42:43]
	v_mov_b32_e32 v8, v6
	v_mov_b32_e32 v9, v4
	v_pk_mul_f32 v[10:11], v[10:11], v[52:53]
	v_mov_b32_e32 v105, v50
	v_pk_fma_f32 v[52:53], v[44:45], v[8:9], v[10:11] neg_lo:[0,0,1] neg_hi:[0,0,1]
	v_mov_b32_e32 v8, v4
	v_mov_b32_e32 v9, v7
	v_pk_mul_f32 v[8:9], v[54:55], v[8:9]
	v_mov_b32_e32 v4, v5
	v_mov_b32_e32 v5, v6
	v_pk_fma_f32 v[44:45], v[98:99], v[4:5], v[8:9]
	v_pk_mov_b32 v[6:7], v[90:91], v[64:65] op_sel:[1,0]
	v_mov_b32_e32 v8, v3
	v_mov_b32_e32 v9, v1
	v_mov_b32_e32 v4, v2
	v_mov_b32_e32 v5, v0
	v_pk_mul_f32 v[6:7], v[6:7], v[8:9]
	v_mov_b32_e32 v98, v53
	v_pk_fma_f32 v[54:55], v[46:47], v[4:5], v[6:7] neg_lo:[0,0,1] neg_hi:[0,0,1]
	v_mov_b32_e32 v4, v0
	v_mov_b32_e32 v5, v3
	v_pk_mul_f32 v[4:5], v[64:65], v[4:5]
	v_mov_b32_e32 v0, v1
	v_mov_b32_e32 v1, v2
	v_pk_fma_f32 v[46:47], v[90:91], v[0:1], v[4:5]
	global_load_dwordx4 v[0:3], v[62:63], off offset:176
	global_load_dwordx4 v[4:7], v[62:63], off offset:160
	global_load_dwordx4 v[8:11], v[62:63], off offset:144
	global_load_dwordx4 v[90:93], v[62:63], off offset:128
	v_pk_mov_b32 v[64:65], v[88:89], v[66:67] op_sel:[1,0]
	v_mov_b32_e32 v106, v51
	v_mov_b32_e32 v114, v49
	s_waitcnt vmcnt(0)
; DI unsigned cvtpk(float lo, float hi) { unsigned r; asm volatile("v_cvt_pk_bf16_f32 %0, %1, %2" : "=v"(r) : "v"(lo), "v"(hi)); return r; }
; DI void attn_dense_body(const bf16_t* __restrict__ Qb, const bf16_t* __restrict__ Kh, const bf16_t* __restrict__ Vh, ...
;     ...
;     if (rope_t0 >= 0) { const int t = rope_t0 + wid * QBLK + r32;
; #pragma unroll
;       for (int half = 0; half < 2; ++half) { const int pos = half ? (t & 63) : (t >> 6);
; #pragma unroll
;         for (int dp = 0; dp < 2; ++dp) { const f32x4* cp = (const f32x4*)(ropeA + pos * 32 + dp * 16 + hi * 8);
; #pragma unroll
;           for (int e2 = 0; e2 < 4; ++e2) { const f32x4 cs = cp[e2];
;             const int da = half * 4 + dp, db = da + 2;
;             float x1 = xf[da][2 * e2], x2 = xf[db][2 * e2]; xf[da][2 * e2] = x1 * cs[0] - x2 * cs[1]; xf[db][2 * e2] = x1 * cs[1] + x2 * cs[0];
;             x1 = xf[da][2 * e2 + 1]; x2 = xf[db][2 * e2 + 1]; xf[da][2 * e2 + 1] = x1 * cs[2] - x2 * cs[3]; xf[db][2 * e2 + 1] = x1 * cs[3] + x2 * cs[2]; } } } }
; #pragma unroll
;     for (int d0 = 0; d0 < 8; ++d0) { u32x4 w = {cvtpk(xf[d0][0], xf[d0][1]), cvtpk(xf[d0][2], xf[d0][3]), cvtpk(xf[d0][4], xf[d0][5]), cvtpk(xf[d0][6], xf[d0][7])}; qr[d0] = *reinterpret_cast<bf16x8*>(&w); }
	v_mov_b32_e32 v94, v93
	v_mov_b32_e32 v95, v91
	v_mov_b32_e32 v62, v92
	v_mov_b32_e32 v63, v90
	v_pk_mul_f32 v[64:65], v[64:65], v[94:95]
	s_nop 0
	v_pk_fma_f32 v[64:65], v[56:57], v[62:63], v[64:65] neg_lo:[0,0,1] neg_hi:[0,0,1]
	v_mov_b32_e32 v56, v90
	v_mov_b32_e32 v57, v93
	v_pk_mul_f32 v[56:57], v[66:67], v[56:57]
	v_mov_b32_e32 v62, v91
	v_mov_b32_e32 v63, v92
	v_pk_fma_f32 v[56:57], v[88:89], v[62:63], v[56:57]
	v_pk_mov_b32 v[66:67], v[86:87], v[72:73] op_sel:[1,0]
	v_mov_b32_e32 v88, v11
	v_mov_b32_e32 v89, v9
	v_mov_b32_e32 v62, v10
	v_mov_b32_e32 v63, v8
	v_pk_mul_f32 v[66:67], v[66:67], v[88:89]
	v_mov_b32_e32 v88, v65
	v_pk_fma_f32 v[66:67], v[58:59], v[62:63], v[66:67] neg_lo:[0,0,1] neg_hi:[0,0,1]
	v_mov_b32_e32 v58, v8
	v_mov_b32_e32 v59, v11
	v_pk_mul_f32 v[58:59], v[72:73], v[58:59]
	v_mov_b32_e32 v8, v9
	v_mov_b32_e32 v9, v10
	v_pk_mov_b32 v[10:11], v[84:85], v[78:79] op_sel:[1,0]
	v_mov_b32_e32 v62, v7
	v_mov_b32_e32 v63, v5
	v_pk_fma_f32 v[58:59], v[86:87], v[8:9], v[58:59]
	v_mov_b32_e32 v8, v6
	v_mov_b32_e32 v9, v4
	v_pk_mul_f32 v[10:11], v[10:11], v[62:63]
	v_mov_b32_e32 v86, v67
	v_pk_fma_f32 v[72:73], v[60:61], v[8:9], v[10:11] neg_lo:[0,0,1] neg_hi:[0,0,1]
	v_mov_b32_e32 v8, v4
	v_mov_b32_e32 v9, v7
	v_pk_mul_f32 v[8:9], v[78:79], v[8:9]
	v_mov_b32_e32 v4, v5
	v_mov_b32_e32 v5, v6
	v_pk_fma_f32 v[60:61], v[84:85], v[4:5], v[8:9]
	v_pk_mov_b32 v[6:7], v[82:83], v[80:81] op_sel:[1,0]
	v_mov_b32_e32 v8, v3
	v_mov_b32_e32 v9, v1
	v_mov_b32_e32 v4, v2
	v_mov_b32_e32 v5, v0
	v_pk_mul_f32 v[6:7], v[6:7], v[8:9]
	v_mov_b32_e32 v84, v73
	v_pk_fma_f32 v[78:79], v[14:15], v[4:5], v[6:7] neg_lo:[0,0,1] neg_hi:[0,0,1]
	v_mov_b32_e32 v4, v0
	v_mov_b32_e32 v5, v3
	v_pk_mul_f32 v[4:5], v[80:81], v[4:5]
	v_mov_b32_e32 v0, v1
	v_mov_b32_e32 v1, v2
	v_pk_fma_f32 v[62:63], v[82:83], v[0:1], v[4:5]
	v_lshlrev_b32_e32 v0, 8, v96
	v_and_b32_e32 v0, 0x3f00, v0
	v_mov_b32_e32 v1, v181
	v_lshl_add_u64 v[12:13], v[12:13], 0, v[0:1]
	global_load_dwordx4 v[0:3], v[12:13], off offset:48
	global_load_dwordx4 v[4:7], v[12:13], off offset:32
	global_load_dwordx4 v[8:11], v[12:13], off offset:16
	global_load_dwordx4 v[80:83], v[12:13], off
	v_mov_b32_e32 v73, v66
	v_mov_b32_e32 v67, v64
	v_mov_b32_e32 v65, v54
	v_mov_b32_e32 v90, v55
	v_mov_b32_e32 v55, v52
	s_waitcnt vmcnt(0)
	v_mov_b32_e32 v15, v82
	v_mov_b32_e32 v82, v81
	v_mov_b32_e32 v14, v80
	v_pk_mul_f32 v[80:81], v[28:29], v[82:83]
	s_nop 0
	v_pk_fma_f32 v[80:81], v[76:77], v[14:15], v[80:81] neg_lo:[0,0,1] neg_hi:[0,0,1]
	v_pk_mul_f32 v[14:15], v[28:29], v[14:15]
	s_nop 0
	v_pk_fma_f32 v[28:29], v[76:77], v[82:83], v[14:15]
	v_mov_b32_e32 v15, v10
	v_mov_b32_e32 v10, v9
	v_mov_b32_e32 v14, v8
	v_pk_mul_f32 v[8:9], v[30:31], v[10:11]
	v_mov_b32_e32 v82, v79
	v_pk_fma_f32 v[76:77], v[74:75], v[14:15], v[8:9] neg_lo:[0,0,1] neg_hi:[0,0,1]
	v_pk_mul_f32 v[8:9], v[30:31], v[14:15]
	v_mov_b32_e32 v79, v72
	v_pk_fma_f32 v[30:31], v[74:75], v[10:11], v[8:9]
	v_mov_b32_e32 v9, v6
	v_mov_b32_e32 v6, v5
	v_mov_b32_e32 v8, v4
	v_pk_mul_f32 v[4:5], v[18:19], v[6:7]
	s_nop 0
	v_pk_fma_f32 v[74:75], v[70:71], v[8:9], v[4:5] neg_lo:[0,0,1] neg_hi:[0,0,1]
	v_pk_mul_f32 v[4:5], v[18:19], v[8:9]
	s_nop 0
	v_pk_fma_f32 v[18:19], v[70:71], v[6:7], v[4:5]
	v_mov_b32_e32 v5, v2
	v_mov_b32_e32 v2, v1
	v_mov_b32_e32 v4, v0
	v_pk_mul_f32 v[0:1], v[20:21], v[2:3]
	s_nop 0
	v_pk_fma_f32 v[70:71], v[68:69], v[4:5], v[0:1] neg_lo:[0,0,1] neg_hi:[0,0,1]
	v_pk_mul_f32 v[0:1], v[20:21], v[4:5]
	s_nop 0
	v_pk_fma_f32 v[20:21], v[68:69], v[2:3], v[0:1]
	global_load_dwordx4 v[0:3], v[12:13], off offset:176
	global_load_dwordx4 v[4:7], v[12:13], off offset:160
	global_load_dwordx4 v[8:11], v[12:13], off offset:144
	s_nop 0
	global_load_dwordx4 v[12:15], v[12:13], off offset:128
	s_waitcnt vmcnt(0)
	v_mov_b32_e32 v68, v12
	v_mov_b32_e32 v69, v14
	v_mov_b32_e32 v14, v13
	v_pk_mul_f32 v[12:13], v[22:23], v[14:15]
	v_pk_mul_f32 v[22:23], v[22:23], v[68:69]
	v_pk_fma_f32 v[12:13], v[38:39], v[68:69], v[12:13] neg_lo:[0,0,1] neg_hi:[0,0,1]
	v_pk_fma_f32 v[22:23], v[38:39], v[14:15], v[22:23]
	v_mov_b32_e32 v15, v10
	v_mov_b32_e32 v10, v9
	v_mov_b32_e32 v14, v8
	v_pk_mul_f32 v[8:9], v[26:27], v[10:11]
	v_mov_b64_e32 v[38:39], v[12:13]
	v_pk_fma_f32 v[8:9], v[36:37], v[14:15], v[8:9] neg_lo:[0,0,1] neg_hi:[0,0,1]
	v_pk_mul_f32 v[14:15], v[26:27], v[14:15]
	v_mov_b64_e32 v[68:69], v[70:71]
	v_pk_fma_f32 v[26:27], v[36:37], v[10:11], v[14:15]
	v_mov_b32_e32 v11, v6
	v_mov_b32_e32 v6, v5
	v_mov_b32_e32 v10, v4
	v_pk_mul_f32 v[4:5], v[16:17], v[6:7]
	v_mov_b64_e32 v[36:37], v[8:9]
	v_pk_fma_f32 v[4:5], v[34:35], v[10:11], v[4:5] neg_lo:[0,0,1] neg_hi:[0,0,1]
	v_pk_mul_f32 v[10:11], v[16:17], v[10:11]
	v_mov_b64_e32 v[70:71], v[74:75]
	v_pk_fma_f32 v[16:17], v[34:35], v[6:7], v[10:11]
	v_mov_b32_e32 v7, v2
	v_mov_b32_e32 v2, v1
	v_mov_b32_e32 v6, v0
	v_pk_mul_f32 v[0:1], v[24:25], v[2:3]
	v_mov_b64_e32 v[74:75], v[76:77]
	v_pk_fma_f32 v[0:1], v[32:33], v[6:7], v[0:1] neg_lo:[0,0,1] neg_hi:[0,0,1]
	v_pk_mul_f32 v[6:7], v[24:25], v[6:7]
	v_mov_b64_e32 v[76:77], v[80:81]
	v_pk_fma_f32 v[24:25], v[32:33], v[2:3], v[6:7]
	v_mov_b64_e32 v[34:35], v[4:5]
	v_mov_b64_e32 v[32:33], v[0:1]
	v_mov_b32_e32 v81, v78
	s_branch .LBB0_834
